# same as previous + code size delta padded to a multiple of 256 bytes (placement control)
# speedup vs baseline: 1.0082x; 1.0082x over previous
; __device__ __forceinline__ CvtTile cvt_decode3(const Args& a, int t) {
;     CvtTile c; c.src = a.in[18]; c.dst = nullptr; c.gain = a.in[17]; c.ldw = 0; c.ldt = 0; c.valid = 0; c.has_gain = 0;
;     static_assert(CV_DN + CV_PA <= NB * LH * 4 * MB_STEPS * NWAVES, "third conversion slot");
;     if (t < 0) return c;
;     if (t < CV_DN) { const int kb = t % (FFW / 32), nb = t / (FFW / 32); c.src = a.in[21] + (size_t)(32 * kb) * DM + 32 * nb; c.dst = (bf16*)(a.ws + WS_WDN) + (size_t)(32 * nb) * FFW + 32 * kb; c.ldw = DM; c.ldt = FFW; c.valid = 1; return c; }
;     if ((t -= CV_DN) < CV_PA) { const int kb = t % (SGW / 32), nb = t / (SGW / 32); c.src = a.in[14] + (size_t)(32 * kb) * DM + 32 * nb; c.dst = (bf16*)(a.ws + WS_PA) + (size_t)(32 * nb) * LW + 32 * kb; c.ldw = DM; c.ldt = LW; c.valid = 1; return c; }
;     return c;
.Lpre_663:
	v_readlane_b32 s52, v238, 28
	v_readlane_b32 s56, v238, 32
	v_readlane_b32 s57, v238, 33
	s_mov_b64 s[70:71], 0
	s_mov_b64 s[16:17], -1
	s_mov_b64 s[28:29], 0
	v_readlane_b32 s53, v238, 29
	v_readlane_b32 s54, v238, 30
	v_readlane_b32 s55, v238, 31
	v_readlane_b32 s58, v238, 34
	v_readlane_b32 s59, v238, 35
	v_readlane_b32 s60, v238, 36
	v_readlane_b32 s61, v238, 37
	v_readlane_b32 s62, v238, 38
	v_readlane_b32 s63, v238, 39
	v_readlane_b32 s64, v238, 40
	v_readlane_b32 s65, v238, 41
	v_readlane_b32 s66, v238, 42
	v_readlane_b32 s67, v238, 43
	s_mov_b64 s[38:39], s[56:57]
	s_andn2_b64 vcc, exec, s[26:27]
	s_mov_b64 s[26:27], s[70:71]
	s_cbranch_vccz .Lpre_650
	s_branch .Lpre_651
	s_nop 0
	s_nop 0
	s_nop 0
	s_nop 0
	s_nop 0
	s_nop 0
	s_nop 0
	s_nop 0
	s_nop 0
	s_nop 0
